# ssd3: first 9 staging loads of an item's second half issued at the end of the first half's staging (land during its compute loop)
# baseline (speedup 1.0000x reference)
.LBB0_39:
	v_readlane_b32 s6, v255, 8
	s_xor_b64 s[26:27], s[0:1], -1
	s_lshl_b32 s0, s4, 7
	v_readlane_b32 s7, v255, 9
	v_mov_b32_e32 v73, v179
	s_or_b32 s66, s6, s0
	v_readlane_b32 s6, v255, 18
	v_lshlrev_b32_e32 v66, 4, v73
	v_ashrrev_i32_e32 v74, 4, v73
	v_and_b32_e32 v66, 0xf0, v66
	v_mov_b32_e32 v67, v1
	v_readlane_b32 s7, v255, 19
	v_ashrrev_i32_e32 v75, 31, v74
	v_add_u32_e32 v72, 32, v66
	v_lshl_add_u64 v[70:71], s[6:7], 0, v[66:67]
	v_lshl_add_u64 v[66:67], s[66:67], 0, v[74:75]
	v_lshlrev_b64 v[66:67], 13, v[66:67]
	v_lshl_add_u64 v[66:67], v[70:71], 0, v[66:67]
	s_cmp_eq_u32 s4, 0
	s_cbranch_scc0 .Ls3pf_g0
	global_load_dwordx4 v[200:203], v[66:67], off
.Ls3pf_g0:
	s_movk_i32 s1, 0x110
	v_mad_u64_u32 v[74:75], s[6:7], v74, s1, v[72:73]
	v_mov_b32_e32 v226, v74
	s_cmp_lt_u32 s4, s35
	s_cselect_b64 s[54:55], -1, 0
	s_cmp_eq_u32 s4, s35
	s_cselect_b64 s[36:37], -1, 0
	s_cmp_gt_u32 s4, s35
	s_movk_i32 s28, 0x110
	s_cselect_b64 s[38:39], -1, 0
	v_or_b32_e32 v84, s0, v150
	v_add_u32_e32 v66, 0x200, v73
	v_ashrrev_i32_e32 v74, 4, v66
	v_ashrrev_i32_e32 v75, 31, v74
	v_lshl_add_u64 v[66:67], s[66:67], 0, v[74:75]
	v_lshlrev_b64 v[66:67], 13, v[66:67]
	v_lshl_add_u64 v[66:67], v[70:71], 0, v[66:67]
	s_cmp_eq_u32 s4, 0
	s_cbranch_scc0 .Ls3pf_g1
	global_load_dwordx4 v[204:207], v[66:67], off
.Ls3pf_g1:
	v_add_u32_e32 v66, 0x400, v73
	v_ashrrev_i32_e32 v74, 4, v66
	v_ashrrev_i32_e32 v75, 31, v74
	v_lshl_add_u64 v[66:67], s[66:67], 0, v[74:75]
	v_lshlrev_b64 v[66:67], 13, v[66:67]
	v_lshl_add_u64 v[66:67], v[70:71], 0, v[66:67]
	s_cmp_eq_u32 s4, 0
	s_cbranch_scc0 .Ls3pf_g2
	global_load_dwordx4 v[208:211], v[66:67], off
.Ls3pf_g2:
	v_add_u32_e32 v66, 0x600, v73
	v_ashrrev_i32_e32 v74, 4, v66
	v_ashrrev_i32_e32 v75, 31, v74
	v_lshl_add_u64 v[66:67], s[66:67], 0, v[74:75]
	v_lshlrev_b64 v[66:67], 13, v[66:67]
	v_lshl_add_u64 v[66:67], v[70:71], 0, v[66:67]
	s_cmp_eq_u32 s4, 0
	s_cbranch_scc0 .Ls3pf_g3
	global_load_dwordx4 v[212:215], v[66:67], off
.Ls3pf_g3:
	v_mov_b32_e32 v68, v179
	v_mov_b32_e32 v67, s67
	v_and_b32_e32 v70, 0x7f, v68
	v_or_b32_e32 v66, s66, v70
	v_ashrrev_i32_e32 v68, 1, v68
	v_lshlrev_b64 v[66:67], 13, v[66:67]
	v_and_b32_e32 v68, 0xffffffc0, v68
	v_lshl_add_u64 v[66:67], s[2:3], 0, v[66:67]
	v_ashrrev_i32_e32 v69, 31, v68
	v_lshl_add_u64 v[66:67], v[68:69], 1, v[66:67]
	v_mul_lo_u32 v72, v68, s1
	v_lshlrev_b32_e32 v73, 1, v70
	s_cmp_eq_u32 s4, 0
	s_cbranch_scc0 .Ls3pf_g4
	global_load_dwordx4 v[130:133], v[66:67], off
.Ls3pf_g4:
	v_readlane_b32 s1, v254, 4
	s_mov_b32 s66, 0
	s_nop 0
	v_add3_u32 v74, s1, v72, v73
	v_add3_u32 v72, s1, v73, v72
	s_cmp_eq_u32 s4, 0
	s_cbranch_scc0 .Ls3pf_g5
	global_load_dwordx4 v[134:137], v[66:67], off offset:16
	global_load_dwordx4 v[138:141], v[66:67], off offset:32
	global_load_dwordx4 v[192:195], v[66:67], off offset:48
	global_load_dwordx4 v[222:225], v[66:67], off offset:64
.Ls3pf_g5:
	s_barrier
	s_waitcnt vmcnt(8)
	ds_write_b128 v226, v[200:203] offset:34816
	global_load_dwordx4 v[200:203], v[66:67], off offset:80
	s_waitcnt vmcnt(8)
	ds_write_b128 v226, v[204:207] offset:43520
	global_load_dwordx4 v[204:207], v[66:67], off offset:96
	s_waitcnt vmcnt(8)
	ds_write_b128 v226, v[208:211] offset:52224
	global_load_dwordx4 v[208:211], v[66:67], off offset:112
	s_waitcnt vmcnt(8)
	ds_write_b128 v226, v[212:215] offset:60928
	s_waitcnt vmcnt(7)
	ds_write_b16 v74, v130
	ds_write_b16_d16_hi v72, v130 offset:272
	ds_write_b16 v72, v131 offset:544
	ds_write_b16_d16_hi v72, v131 offset:816
	ds_write_b16 v72, v132 offset:1088
	ds_write_b16_d16_hi v72, v132 offset:1360
	ds_write_b16 v74, v133 offset:1632
	ds_write_b16_d16_hi v72, v133 offset:1904
	s_waitcnt vmcnt(6)
	ds_write_b16 v72, v134 offset:2176
	ds_write_b16_d16_hi v72, v134 offset:2448
	ds_write_b16 v74, v135 offset:2720
	ds_write_b16_d16_hi v72, v135 offset:2992
	ds_write_b16 v72, v136 offset:3264
	ds_write_b16_d16_hi v72, v136 offset:3536
	ds_write_b16 v74, v137 offset:3808
	ds_write_b16_d16_hi v72, v137 offset:4080
	s_waitcnt vmcnt(5)
	ds_write_b16 v72, v138 offset:4352
	ds_write_b16_d16_hi v72, v138 offset:4624
	ds_write_b16 v74, v139 offset:4896
	ds_write_b16_d16_hi v72, v139 offset:5168
	ds_write_b16 v72, v140 offset:5440
	ds_write_b16_d16_hi v72, v140 offset:5712
	ds_write_b16 v74, v141 offset:5984
	ds_write_b16_d16_hi v72, v141 offset:6256
	s_waitcnt vmcnt(4)
	ds_write_b16 v72, v192 offset:6528
	ds_write_b16_d16_hi v72, v192 offset:6800
	ds_write_b16 v74, v193 offset:7072
	ds_write_b16_d16_hi v72, v193 offset:7344
	ds_write_b16 v72, v194 offset:7616
	ds_write_b16_d16_hi v72, v194 offset:7888
	ds_write_b16 v74, v195 offset:8160
	ds_write_b16_d16_hi v72, v195 offset:8432
	s_waitcnt vmcnt(3)
	ds_write_b16 v72, v222 offset:8704
	ds_write_b16_d16_hi v72, v222 offset:8976
	ds_write_b16 v74, v223 offset:9248
	ds_write_b16_d16_hi v72, v223 offset:9520
	ds_write_b16 v72, v224 offset:9792
	ds_write_b16_d16_hi v72, v224 offset:10064
	ds_write_b16 v74, v225 offset:10336
	ds_write_b16_d16_hi v72, v225 offset:10608
	s_waitcnt vmcnt(2)
	ds_write_b16 v72, v200 offset:10880
	ds_write_b16_d16_hi v72, v200 offset:11152
	ds_write_b16 v74, v201 offset:11424
	ds_write_b16_d16_hi v72, v201 offset:11696
	ds_write_b16 v72, v202 offset:11968
	ds_write_b16_d16_hi v72, v202 offset:12240
	ds_write_b16 v74, v203 offset:12512
	ds_write_b16_d16_hi v72, v203 offset:12784
	s_waitcnt vmcnt(1)
	ds_write_b16 v72, v204 offset:13056
	ds_write_b16_d16_hi v72, v204 offset:13328
	ds_write_b16 v74, v205 offset:13600
	ds_write_b16_d16_hi v72, v205 offset:13872
	ds_write_b16 v72, v206 offset:14144
	ds_write_b16_d16_hi v72, v206 offset:14416
	ds_write_b16 v74, v207 offset:14688
	ds_write_b16_d16_hi v72, v207 offset:14960
	s_waitcnt vmcnt(0)
	ds_write_b16 v72, v208 offset:15232
	ds_write_b16_d16_hi v72, v208 offset:15504
	ds_write_b16 v74, v209 offset:15776
	ds_write_b16_d16_hi v72, v209 offset:16048
	ds_write_b16 v72, v210 offset:16320
	ds_write_b16_d16_hi v72, v210 offset:16592
	ds_write_b16 v74, v211 offset:16864
	ds_write_b16_d16_hi v72, v211 offset:17136
	s_cmp_eq_u32 s4, 0
	s_cbranch_scc0 .Ls3pf_skip
	v_readlane_b32 s6, v255, 8
	s_nop 0
	s_or_b32 s0, s6, 0x80
	s_mov_b32 s1, s67
	v_readlane_b32 s6, v255, 18
	v_readlane_b32 s7, v255, 19
	v_lshlrev_b32_e32 v66, 4, v179
	v_ashrrev_i32_e32 v74, 4, v179
	v_and_b32_e32 v66, 0xf0, v66
	v_mov_b32_e32 v67, v1
	v_ashrrev_i32_e32 v75, 31, v74
	v_lshl_add_u64 v[70:71], s[6:7], 0, v[66:67]
	v_lshl_add_u64 v[66:67], s[0:1], 0, v[74:75]
	v_lshlrev_b64 v[66:67], 13, v[66:67]
	v_lshl_add_u64 v[66:67], v[70:71], 0, v[66:67]
	global_load_dwordx4 v[200:203], v[66:67], off
	v_add_u32_e32 v66, 0x200, v179
	v_ashrrev_i32_e32 v74, 4, v66
	v_ashrrev_i32_e32 v75, 31, v74
	v_lshl_add_u64 v[66:67], s[0:1], 0, v[74:75]
	v_lshlrev_b64 v[66:67], 13, v[66:67]
	v_lshl_add_u64 v[66:67], v[70:71], 0, v[66:67]
	global_load_dwordx4 v[204:207], v[66:67], off
	v_add_u32_e32 v66, 0x400, v179
	v_ashrrev_i32_e32 v74, 4, v66
	v_ashrrev_i32_e32 v75, 31, v74
	v_lshl_add_u64 v[66:67], s[0:1], 0, v[74:75]
	v_lshlrev_b64 v[66:67], 13, v[66:67]
	v_lshl_add_u64 v[66:67], v[70:71], 0, v[66:67]
	global_load_dwordx4 v[208:211], v[66:67], off
	v_add_u32_e32 v66, 0x600, v179
	v_ashrrev_i32_e32 v74, 4, v66
	v_ashrrev_i32_e32 v75, 31, v74
	v_lshl_add_u64 v[66:67], s[0:1], 0, v[74:75]
	v_lshlrev_b64 v[66:67], 13, v[66:67]
	v_lshl_add_u64 v[66:67], v[70:71], 0, v[66:67]
	global_load_dwordx4 v[212:215], v[66:67], off
	v_mov_b32_e32 v67, s1
	v_and_b32_e32 v70, 0x7f, v179
	v_or_b32_e32 v66, s0, v70
	v_ashrrev_i32_e32 v68, 1, v179
	v_lshlrev_b64 v[66:67], 13, v[66:67]
	v_and_b32_e32 v68, 0xffffffc0, v68
	v_lshl_add_u64 v[66:67], s[2:3], 0, v[66:67]
	v_ashrrev_i32_e32 v69, 31, v68
	v_lshl_add_u64 v[66:67], v[68:69], 1, v[66:67]
	global_load_dwordx4 v[130:133], v[66:67], off
	global_load_dwordx4 v[134:137], v[66:67], off offset:16
	global_load_dwordx4 v[138:141], v[66:67], off offset:32
	global_load_dwordx4 v[192:195], v[66:67], off offset:48
	global_load_dwordx4 v[222:225], v[66:67], off offset:64
.Ls3pf_skip:
	s_waitcnt lgkmcnt(0)
	s_barrier
	s_branch .LBB0_42
